# m3 gate preamble: MST load issued with the gate loads
# speedup vs baseline: 1.0004x; 1.0004x over previous
.LBB0_449:
	s_ashr_i32 s2, s39, 10
	s_and_b32 s41, s39, 0x7f
	s_ashr_i32 s3, s2, 31
	v_mov_b32_e32 v23, v194
	s_lshl_b64 s[34:35], s[2:3], 13
	s_lshl_b32 s2, s41, 6
	s_bfe_u32 s42, s39, 0x30007
	v_readfirstlane_b32 s40, v23
	s_or_b32 s34, s34, s2
	s_cmp_gt_u32 s40, 63
	v_and_b32_e32 v22, 63, v23
	s_cbranch_scc1 .LBB0_451
	v_or_b32_e32 v0, s34, v22
	v_mov_b32_e32 v1, s35
	v_lshlrev_b64 v[0:1], 6, v[0:1]
	v_lshl_add_u64 v[0:1], s[30:31], 0, v[0:1]
	s_lshl_b32 s86, s42, 2
	v_lshl_add_u64 v[0:1], v[0:1], 0, s[86:87]
	v_mov_b32_e32 v3, s86
	global_load_dword v2, v[0:1], off offset:32
	global_load_dword v4, v3, s[26:27]
	s_nop 0
	global_load_dword v0, v[0:1], off
	s_nop 0
	global_load_dword v1, v3, s[28:29]
	s_lshl_b32 s98, s39, 4
	s_add_u32 s98, s0, s98
	s_addc_u32 s99, s1, 0
	v_mov_b32_e32 v41, 0x18100000
	global_load_dword v42, v41, s[98:99] offset:8
	s_mov_b32 s2, 0x3f317218
	s_waitcnt vmcnt(2)
	v_add_f32_e32 v2, v2, v4
	s_waitcnt vmcnt(0)
	v_add_f32_e32 v1, v0, v1
	v_min_f32_e32 v0, 0, v2
	v_mul_f32_e64 v2, |v2|, s79
	v_exp_f32_e32 v4, v2
	s_nop 0
	v_add_f32_e32 v5, 1.0, v4
	v_add_f32_e32 v2, -1.0, v5
	v_sub_f32_e32 v3, v2, v5
	v_add_f32_e32 v3, 1.0, v3
	v_sub_f32_e32 v2, v4, v2
	v_add_f32_e32 v6, v2, v3
	v_frexp_mant_f32_e32 v2, v5
	v_cmp_gt_f32_e32 vcc, s85, v2
	v_cvt_f64_f32_e32 v[2:3], v5
	v_frexp_exp_i32_f64_e32 v2, v[2:3]
	v_subbrev_co_u32_e32 v2, vcc, 0, v2, vcc
	v_sub_u32_e32 v3, 0, v2
	v_ldexp_f32 v5, v5, v3
	v_ldexp_f32 v3, v6, v3
	v_add_f32_e32 v6, -1.0, v5
	v_add_f32_e32 v7, 1.0, v6
	v_sub_f32_e32 v7, v5, v7
	v_add_f32_e32 v7, v3, v7
	v_add_f32_e32 v8, v6, v7
	v_sub_f32_e32 v6, v8, v6
	v_sub_f32_e32 v6, v7, v6
	v_add_f32_e32 v7, 1.0, v5
	v_add_f32_e32 v9, -1.0, v7
	v_sub_f32_e32 v5, v5, v9
	v_add_f32_e32 v3, v3, v5
	v_add_f32_e32 v5, v7, v3
	v_sub_f32_e32 v7, v5, v7
	v_sub_f32_e32 v3, v3, v7
	v_rcp_f32_e32 v7, v5
	v_cvt_f32_i32_e32 v2, v2
	v_mul_f32_e32 v9, v8, v7
	v_mul_f32_e32 v10, v5, v9
	v_fma_f32 v11, v9, v5, -v10
	v_fmac_f32_e32 v11, v9, v3
	v_add_f32_e32 v12, v10, v11
	v_sub_f32_e32 v13, v8, v12
	v_sub_f32_e32 v8, v8, v13
	v_sub_f32_e32 v10, v12, v10
	v_sub_f32_e32 v8, v8, v12
	v_add_f32_e32 v6, v6, v8
	v_sub_f32_e32 v8, v10, v11
	v_add_f32_e32 v6, v8, v6
	v_add_f32_e32 v8, v13, v6
	v_mul_f32_e32 v10, v7, v8
	v_mul_f32_e32 v11, v5, v10
	v_fma_f32 v5, v10, v5, -v11
	v_fmac_f32_e32 v5, v10, v3
	v_sub_f32_e32 v3, v13, v8
	v_add_f32_e32 v3, v6, v3
	v_add_f32_e32 v6, v11, v5
	v_sub_f32_e32 v12, v8, v6
	v_sub_f32_e32 v8, v8, v12
	v_sub_f32_e32 v11, v6, v11
	v_sub_f32_e32 v6, v8, v6
	v_add_f32_e32 v3, v3, v6
	v_sub_f32_e32 v5, v11, v5
	v_add_f32_e32 v3, v5, v3
	v_add_f32_e32 v5, v9, v10
	v_add_f32_e32 v3, v12, v3
	v_sub_f32_e32 v6, v5, v9
	v_mul_f32_e32 v3, v7, v3
	v_sub_f32_e32 v6, v10, v6
	v_add_f32_e32 v3, v6, v3
	v_mul_f32_e32 v9, 0x3f317218, v2
	v_add_f32_e32 v6, v5, v3
	v_fma_f32 v10, v2, s2, -v9
	v_mul_f32_e32 v7, v6, v6
	v_fmac_f32_e32 v10, 0xb102e308, v2
	v_sub_f32_e32 v2, v6, v5
	v_fmamk_f32 v8, v7, 0x3e9b6dac, v200
	v_sub_f32_e32 v2, v3, v2
	v_add_f32_e32 v3, v9, v10
	v_fmaak_f32 v8, v7, v8, 0x3f2aaada
	v_sub_f32_e32 v5, v3, v9
	v_ldexp_f32 v9, v6, 1
	v_mul_f32_e32 v6, v6, v7
	v_mul_f32_e32 v6, v6, v8
	v_add_f32_e32 v7, v9, v6
	v_sub_f32_e32 v8, v7, v9
	v_ldexp_f32 v2, v2, 1
	v_sub_f32_e32 v6, v6, v8
	v_add_f32_e32 v2, v2, v6
	v_add_f32_e32 v6, v7, v2
	v_sub_f32_e32 v7, v6, v7
	v_sub_f32_e32 v2, v2, v7
	v_add_f32_e32 v7, v3, v6
	v_sub_f32_e32 v8, v7, v3
	v_sub_f32_e32 v9, v7, v8
	v_sub_f32_e32 v5, v10, v5
	v_sub_f32_e32 v3, v3, v9
	v_sub_f32_e32 v6, v6, v8
	v_add_f32_e32 v3, v6, v3
	v_add_f32_e32 v6, v5, v2
	v_sub_f32_e32 v8, v6, v5
	v_sub_f32_e32 v9, v6, v8
	v_sub_f32_e32 v5, v5, v9
	v_sub_f32_e32 v2, v2, v8
	v_add_f32_e32 v3, v6, v3
	v_add_f32_e32 v2, v2, v5
	v_add_f32_e32 v5, v7, v3
	v_sub_f32_e32 v6, v5, v7
	v_sub_f32_e32 v3, v3, v6
	v_add_f32_e32 v2, v2, v3
	s_mov_b32 s2, 0x7f800000
	v_add_f32_e32 v2, v5, v2
	v_cmp_neq_f32_e32 vcc, s2, v4
	s_mov_b32 s2, 0x33800000
	v_add_u32_e32 v3, -1, v201
	v_cndmask_b32_e32 v2, v202, v2, vcc
	v_cmp_ngt_f32_e32 vcc, -1.0, v4
	s_nop 1
	v_cndmask_b32_e32 v2, v203, v2, vcc
	v_cmp_neq_f32_e32 vcc, -1.0, v4
	s_nop 1
	v_cndmask_b32_e32 v2, v204, v2, vcc
	v_cmp_lt_f32_e64 vcc, |v4|, s2
	s_lshl_b32 s2, s39, 2
	s_ashr_i32 s3, s2, 31
	v_cndmask_b32_e32 v2, v2, v4, vcc
	v_sub_f32_e32 v0, v0, v2
	v_and_b32_e32 v2, 64, v201
	v_cmp_lt_i32_e32 vcc, v3, v2
	s_lshl_b64 s[2:3], s[2:3], 2
	s_add_u32 s2, s0, s2
	v_cndmask_b32_e32 v3, v3, v201, vcc
	v_lshlrev_b32_e32 v3, 2, v3
	ds_bpermute_b32 v4, v3, v0
	v_cmp_eq_u32_e32 vcc, 0, v22
	s_addc_u32 s3, s1, s3
	s_waitcnt lgkmcnt(0)
	v_add_f32_e32 v4, v0, v4
	v_cndmask_b32_e32 v0, v4, v0, vcc
	v_add_u32_e32 v4, -2, v201
	v_cmp_lt_i32_e64 s[4:5], v4, v2
	s_nop 1
	v_cndmask_b32_e64 v4, v4, v201, s[4:5]
	v_lshlrev_b32_e32 v4, 2, v4
	ds_bpermute_b32 v5, v4, v0
	v_cmp_gt_u32_e64 s[4:5], 2, v22
	s_waitcnt lgkmcnt(0)
	v_add_f32_e32 v5, v0, v5
	v_cndmask_b32_e64 v0, v5, v0, s[4:5]
	v_add_u32_e32 v5, -4, v201
	v_cmp_lt_i32_e64 s[6:7], v5, v2
	s_nop 1
	v_cndmask_b32_e64 v5, v5, v201, s[6:7]
	v_lshlrev_b32_e32 v5, 2, v5
	ds_bpermute_b32 v6, v5, v0
	v_cmp_gt_u32_e64 s[6:7], 4, v22
	s_waitcnt lgkmcnt(0)
	v_add_f32_e32 v6, v0, v6
	v_cndmask_b32_e64 v0, v6, v0, s[6:7]
	v_add_u32_e32 v6, -8, v201
	v_cmp_lt_i32_e64 s[8:9], v6, v2
	s_nop 1
	v_cndmask_b32_e64 v6, v6, v201, s[8:9]
	v_lshlrev_b32_e32 v6, 2, v6
	ds_bpermute_b32 v7, v6, v0
	v_cmp_gt_u32_e64 s[8:9], 8, v22
	s_waitcnt lgkmcnt(0)
	v_add_f32_e32 v7, v0, v7
	v_cndmask_b32_e64 v0, v7, v0, s[8:9]
	v_add_u32_e32 v7, -16, v201
	v_cmp_lt_i32_e64 s[10:11], v7, v2
	s_nop 1
	v_cndmask_b32_e64 v7, v7, v201, s[10:11]
	v_lshlrev_b32_e32 v7, 2, v7
	ds_bpermute_b32 v8, v7, v0
	v_cmp_gt_u32_e64 s[10:11], 16, v22
	s_waitcnt lgkmcnt(0)
	v_add_f32_e32 v8, v0, v8
	v_cndmask_b32_e64 v0, v8, v0, s[10:11]
	v_subrev_u32_e32 v8, 32, v201
	v_cmp_lt_i32_e64 s[12:13], v8, v2
	s_nop 1
	v_cndmask_b32_e64 v2, v8, v201, s[12:13]
	v_lshlrev_b32_e32 v2, 2, v2
	ds_bpermute_b32 v8, v2, v0
	v_cmp_gt_u32_e64 s[12:13], 32, v22
	s_waitcnt lgkmcnt(0)
	v_add_f32_e32 v8, v0, v8
	v_cndmask_b32_e64 v0, v8, v0, s[12:13]
	v_sub_f32_e32 v1, v1, v0
	ds_bpermute_b32 v3, v3, v1
	s_waitcnt lgkmcnt(0)
	v_max_f32_e32 v3, v3, v3
	v_max_f32_e32 v3, v1, v3
	v_cndmask_b32_e32 v3, v3, v1, vcc
	ds_bpermute_b32 v4, v4, v3
	s_waitcnt lgkmcnt(0)
	v_max_f32_e32 v4, v4, v4
	v_max_f32_e32 v4, v3, v4
	v_cndmask_b32_e64 v3, v4, v3, s[4:5]
	ds_bpermute_b32 v4, v5, v3
	s_waitcnt lgkmcnt(0)
	v_max_f32_e32 v4, v4, v4
	v_max_f32_e32 v4, v3, v4
	v_cndmask_b32_e64 v3, v4, v3, s[6:7]
	ds_bpermute_b32 v4, v6, v3
	s_waitcnt lgkmcnt(0)
	v_max_f32_e32 v4, v4, v4
	v_max_f32_e32 v4, v3, v4
	v_cndmask_b32_e64 v3, v4, v3, s[8:9]
	ds_bpermute_b32 v4, v7, v3
	s_waitcnt lgkmcnt(0)
	v_max_f32_e32 v4, v4, v4
	v_max_f32_e32 v4, v3, v4
	v_cndmask_b32_e64 v3, v4, v3, s[10:11]
	ds_bpermute_b32 v2, v2, v3
	v_max_f32_e32 v4, v3, v3
	s_waitcnt lgkmcnt(0)
	v_max_f32_e32 v2, v2, v2
	v_max_f32_e32 v2, v4, v2
	v_cndmask_b32_e64 v2, v2, v3, s[12:13]
	v_max_f32_e32 v2, v2, v2
	s_waitcnt vmcnt(0)
	v_mov_b32_e32 v3, v42
	v_max_f32_e32 v4, v3, v3
	v_max_f32_e32 v2, v4, v2
	v_lshl_add_u32 v4, v22, 2, 0
	v_add_u32_e32 v4, 0x19200, v4
	ds_write2st64_b32 v4, v1, v2 offset1:1
	v_sub_f32_e32 v1, v3, v2
	v_add_f32_e32 v0, v0, v2
	v_mul_f32_e32 v1, 0x3fb8aa3b, v1
	v_mul_f32_e32 v0, 0xbfb8aa3b, v0
	v_exp_f32_e32 v1, v1
	v_exp_f32_e32 v0, v0
	ds_write2st64_b32 v4, v1, v0 offset0:2 offset1:3
